# lambda dot products with 4 loads + in-order fma chain; L2-warm load of the next phase's weights issued behind the arrival barrier instead of being waited for in front of it
# speedup vs baseline: 1.0119x; 1.0001x over previous
.LBB0_12:
	s_waitcnt vmcnt(0)
	s_load_dword s3, s[0:1], 0xbc

.LBB0_158:
	s_load_dwordx8 s[16:23], s[0:1], 0x50
	s_lshl_b32 s8, s30, 6
	s_ashr_i32 s9, s8, 31
	s_lshl_b64 s[26:27], s[8:9], 2
	v_mov_b32_e32 v1, 0
	s_waitcnt lgkmcnt(0)
	s_add_u32 s3, s16, s26
	s_addc_u32 s8, s17, s27
	s_add_u32 s9, s18, s26
	s_addc_u32 s10, s19, s27
	s_add_u32 s11, s20, s26
	s_addc_u32 s14, s21, s27
	s_add_u32 s15, s22, s26
	s_addc_u32 s16, s23, s27
	s_mov_b64 s[26:27], 0
	v_mov_b32_e32 v0, 0
	v_mbcnt_lo_u32_b32 v2, -1, 0
	v_mbcnt_hi_u32_b32 v2, -1, v2
	v_lshlrev_b32_e32 v2, 2, v2
	s_mov_b32 s18, s3
	s_mov_b32 s19, s8
	global_load_dword v6, v2, s[18:19]
	s_mov_b32 s18, s9
	s_mov_b32 s19, s10
	global_load_dword v7, v2, s[18:19]
	s_mov_b32 s18, s11
	s_mov_b32 s19, s14
	global_load_dword v8, v2, s[18:19]
	s_mov_b32 s18, s15
	s_mov_b32 s19, s16
	global_load_dword v9, v2, s[18:19]
	s_waitcnt vmcnt(0)
	v_readlane_b32 s26, v7, 0
	v_readlane_b32 s27, v9, 0
	v_readlane_b32 s18, v6, 0
	v_readlane_b32 s19, v8, 0
	v_mov_b32_e32 v10, s26
	v_mov_b32_e32 v11, s27
	v_fma_f32 v1, s18, v10, v1
	v_fma_f32 v0, s19, v11, v0
	v_readlane_b32 s26, v7, 1
	v_readlane_b32 s27, v9, 1
	v_readlane_b32 s18, v6, 1
	v_readlane_b32 s19, v8, 1
	v_mov_b32_e32 v10, s26
	v_mov_b32_e32 v11, s27
	v_fma_f32 v1, s18, v10, v1
	v_fma_f32 v0, s19, v11, v0
	v_readlane_b32 s26, v7, 2
	v_readlane_b32 s27, v9, 2
	v_readlane_b32 s18, v6, 2
	v_readlane_b32 s19, v8, 2
	v_mov_b32_e32 v10, s26
	v_mov_b32_e32 v11, s27
	v_fma_f32 v1, s18, v10, v1
	v_fma_f32 v0, s19, v11, v0
	v_readlane_b32 s26, v7, 3
	v_readlane_b32 s27, v9, 3
	v_readlane_b32 s18, v6, 3
	v_readlane_b32 s19, v8, 3
	v_mov_b32_e32 v10, s26
	v_mov_b32_e32 v11, s27
	v_fma_f32 v1, s18, v10, v1
	v_fma_f32 v0, s19, v11, v0
	v_readlane_b32 s26, v7, 4
	v_readlane_b32 s27, v9, 4
	v_readlane_b32 s18, v6, 4
	v_readlane_b32 s19, v8, 4
	v_mov_b32_e32 v10, s26
	v_mov_b32_e32 v11, s27
	v_fma_f32 v1, s18, v10, v1
	v_fma_f32 v0, s19, v11, v0
	v_readlane_b32 s26, v7, 5
	v_readlane_b32 s27, v9, 5
	v_readlane_b32 s18, v6, 5
	v_readlane_b32 s19, v8, 5
	v_mov_b32_e32 v10, s26
	v_mov_b32_e32 v11, s27
	v_fma_f32 v1, s18, v10, v1
	v_fma_f32 v0, s19, v11, v0
	v_readlane_b32 s26, v7, 6
	v_readlane_b32 s27, v9, 6
	v_readlane_b32 s18, v6, 6
	v_readlane_b32 s19, v8, 6
	v_mov_b32_e32 v10, s26
	v_mov_b32_e32 v11, s27
	v_fma_f32 v1, s18, v10, v1
	v_fma_f32 v0, s19, v11, v0
	v_readlane_b32 s26, v7, 7
	v_readlane_b32 s27, v9, 7
	v_readlane_b32 s18, v6, 7
	v_readlane_b32 s19, v8, 7
	v_mov_b32_e32 v10, s26
	v_mov_b32_e32 v11, s27
	v_fma_f32 v1, s18, v10, v1
	v_fma_f32 v0, s19, v11, v0
	v_readlane_b32 s26, v7, 8
	v_readlane_b32 s27, v9, 8
	v_readlane_b32 s18, v6, 8
	v_readlane_b32 s19, v8, 8
	v_mov_b32_e32 v10, s26
	v_mov_b32_e32 v11, s27
	v_fma_f32 v1, s18, v10, v1
	v_fma_f32 v0, s19, v11, v0
	v_readlane_b32 s26, v7, 9
	v_readlane_b32 s27, v9, 9
	v_readlane_b32 s18, v6, 9
	v_readlane_b32 s19, v8, 9
	v_mov_b32_e32 v10, s26
	v_mov_b32_e32 v11, s27
	v_fma_f32 v1, s18, v10, v1
	v_fma_f32 v0, s19, v11, v0
	v_readlane_b32 s26, v7, 10
	v_readlane_b32 s27, v9, 10
	v_readlane_b32 s18, v6, 10
	v_readlane_b32 s19, v8, 10
	v_mov_b32_e32 v10, s26
	v_mov_b32_e32 v11, s27
	v_fma_f32 v1, s18, v10, v1
	v_fma_f32 v0, s19, v11, v0
	v_readlane_b32 s26, v7, 11
	v_readlane_b32 s27, v9, 11
	v_readlane_b32 s18, v6, 11
	v_readlane_b32 s19, v8, 11
	v_mov_b32_e32 v10, s26
	v_mov_b32_e32 v11, s27
	v_fma_f32 v1, s18, v10, v1
	v_fma_f32 v0, s19, v11, v0
	v_readlane_b32 s26, v7, 12
	v_readlane_b32 s27, v9, 12
	v_readlane_b32 s18, v6, 12
	v_readlane_b32 s19, v8, 12
	v_mov_b32_e32 v10, s26
	v_mov_b32_e32 v11, s27
	v_fma_f32 v1, s18, v10, v1
	v_fma_f32 v0, s19, v11, v0
	v_readlane_b32 s26, v7, 13
	v_readlane_b32 s27, v9, 13
	v_readlane_b32 s18, v6, 13
	v_readlane_b32 s19, v8, 13
	v_mov_b32_e32 v10, s26
	v_mov_b32_e32 v11, s27
	v_fma_f32 v1, s18, v10, v1
	v_fma_f32 v0, s19, v11, v0
	v_readlane_b32 s26, v7, 14
	v_readlane_b32 s27, v9, 14
	v_readlane_b32 s18, v6, 14
	v_readlane_b32 s19, v8, 14
	v_mov_b32_e32 v10, s26
	v_mov_b32_e32 v11, s27
	v_fma_f32 v1, s18, v10, v1
	v_fma_f32 v0, s19, v11, v0
	v_readlane_b32 s26, v7, 15
	v_readlane_b32 s27, v9, 15
	v_readlane_b32 s18, v6, 15
	v_readlane_b32 s19, v8, 15
	v_mov_b32_e32 v10, s26
	v_mov_b32_e32 v11, s27
	v_fma_f32 v1, s18, v10, v1
	v_fma_f32 v0, s19, v11, v0
	v_readlane_b32 s26, v7, 16
	v_readlane_b32 s27, v9, 16
	v_readlane_b32 s18, v6, 16
	v_readlane_b32 s19, v8, 16
	v_mov_b32_e32 v10, s26
	v_mov_b32_e32 v11, s27
	v_fma_f32 v1, s18, v10, v1
	v_fma_f32 v0, s19, v11, v0
	v_readlane_b32 s26, v7, 17
	v_readlane_b32 s27, v9, 17
	v_readlane_b32 s18, v6, 17
	v_readlane_b32 s19, v8, 17
	v_mov_b32_e32 v10, s26
	v_mov_b32_e32 v11, s27
	v_fma_f32 v1, s18, v10, v1
	v_fma_f32 v0, s19, v11, v0
	v_readlane_b32 s26, v7, 18
	v_readlane_b32 s27, v9, 18
	v_readlane_b32 s18, v6, 18
	v_readlane_b32 s19, v8, 18
	v_mov_b32_e32 v10, s26
	v_mov_b32_e32 v11, s27
	v_fma_f32 v1, s18, v10, v1
	v_fma_f32 v0, s19, v11, v0
	v_readlane_b32 s26, v7, 19
	v_readlane_b32 s27, v9, 19
	v_readlane_b32 s18, v6, 19
	v_readlane_b32 s19, v8, 19
	v_mov_b32_e32 v10, s26
	v_mov_b32_e32 v11, s27
	v_fma_f32 v1, s18, v10, v1
	v_fma_f32 v0, s19, v11, v0
	v_readlane_b32 s26, v7, 20
	v_readlane_b32 s27, v9, 20
	v_readlane_b32 s18, v6, 20
	v_readlane_b32 s19, v8, 20
	v_mov_b32_e32 v10, s26
	v_mov_b32_e32 v11, s27
	v_fma_f32 v1, s18, v10, v1
	v_fma_f32 v0, s19, v11, v0
	v_readlane_b32 s26, v7, 21
	v_readlane_b32 s27, v9, 21
	v_readlane_b32 s18, v6, 21
	v_readlane_b32 s19, v8, 21
	v_mov_b32_e32 v10, s26
	v_mov_b32_e32 v11, s27
	v_fma_f32 v1, s18, v10, v1
	v_fma_f32 v0, s19, v11, v0
	v_readlane_b32 s26, v7, 22
	v_readlane_b32 s27, v9, 22
	v_readlane_b32 s18, v6, 22
	v_readlane_b32 s19, v8, 22
	v_mov_b32_e32 v10, s26
	v_mov_b32_e32 v11, s27
	v_fma_f32 v1, s18, v10, v1
	v_fma_f32 v0, s19, v11, v0
	v_readlane_b32 s26, v7, 23
	v_readlane_b32 s27, v9, 23
	v_readlane_b32 s18, v6, 23
	v_readlane_b32 s19, v8, 23
	v_mov_b32_e32 v10, s26
	v_mov_b32_e32 v11, s27
	v_fma_f32 v1, s18, v10, v1
	v_fma_f32 v0, s19, v11, v0
	v_readlane_b32 s26, v7, 24
	v_readlane_b32 s27, v9, 24
	v_readlane_b32 s18, v6, 24
	v_readlane_b32 s19, v8, 24
	v_mov_b32_e32 v10, s26
	v_mov_b32_e32 v11, s27
	v_fma_f32 v1, s18, v10, v1
	v_fma_f32 v0, s19, v11, v0
	v_readlane_b32 s26, v7, 25
	v_readlane_b32 s27, v9, 25
	v_readlane_b32 s18, v6, 25
	v_readlane_b32 s19, v8, 25
	v_mov_b32_e32 v10, s26
	v_mov_b32_e32 v11, s27
	v_fma_f32 v1, s18, v10, v1
	v_fma_f32 v0, s19, v11, v0
	v_readlane_b32 s26, v7, 26
	v_readlane_b32 s27, v9, 26
	v_readlane_b32 s18, v6, 26
	v_readlane_b32 s19, v8, 26
	v_mov_b32_e32 v10, s26
	v_mov_b32_e32 v11, s27
	v_fma_f32 v1, s18, v10, v1
	v_fma_f32 v0, s19, v11, v0
	v_readlane_b32 s26, v7, 27
	v_readlane_b32 s27, v9, 27
	v_readlane_b32 s18, v6, 27
	v_readlane_b32 s19, v8, 27
	v_mov_b32_e32 v10, s26
	v_mov_b32_e32 v11, s27
	v_fma_f32 v1, s18, v10, v1
	v_fma_f32 v0, s19, v11, v0
	v_readlane_b32 s26, v7, 28
	v_readlane_b32 s27, v9, 28
	v_readlane_b32 s18, v6, 28
	v_readlane_b32 s19, v8, 28
	v_mov_b32_e32 v10, s26
	v_mov_b32_e32 v11, s27
	v_fma_f32 v1, s18, v10, v1
	v_fma_f32 v0, s19, v11, v0
	v_readlane_b32 s26, v7, 29
	v_readlane_b32 s27, v9, 29
	v_readlane_b32 s18, v6, 29
	v_readlane_b32 s19, v8, 29
	v_mov_b32_e32 v10, s26
	v_mov_b32_e32 v11, s27
	v_fma_f32 v1, s18, v10, v1
	v_fma_f32 v0, s19, v11, v0
	v_readlane_b32 s26, v7, 30
	v_readlane_b32 s27, v9, 30
	v_readlane_b32 s18, v6, 30
	v_readlane_b32 s19, v8, 30
	v_mov_b32_e32 v10, s26
	v_mov_b32_e32 v11, s27
	v_fma_f32 v1, s18, v10, v1
	v_fma_f32 v0, s19, v11, v0
	v_readlane_b32 s26, v7, 31
	v_readlane_b32 s27, v9, 31
	v_readlane_b32 s18, v6, 31
	v_readlane_b32 s19, v8, 31
	v_mov_b32_e32 v10, s26
	v_mov_b32_e32 v11, s27
	v_fma_f32 v1, s18, v10, v1
	v_fma_f32 v0, s19, v11, v0
	v_readlane_b32 s26, v7, 32
	v_readlane_b32 s27, v9, 32
	v_readlane_b32 s18, v6, 32
	v_readlane_b32 s19, v8, 32
	v_mov_b32_e32 v10, s26
	v_mov_b32_e32 v11, s27
	v_fma_f32 v1, s18, v10, v1
	v_fma_f32 v0, s19, v11, v0
	v_readlane_b32 s26, v7, 33
	v_readlane_b32 s27, v9, 33
	v_readlane_b32 s18, v6, 33
	v_readlane_b32 s19, v8, 33
	v_mov_b32_e32 v10, s26
	v_mov_b32_e32 v11, s27
	v_fma_f32 v1, s18, v10, v1
	v_fma_f32 v0, s19, v11, v0
	v_readlane_b32 s26, v7, 34
	v_readlane_b32 s27, v9, 34
	v_readlane_b32 s18, v6, 34
	v_readlane_b32 s19, v8, 34
	v_mov_b32_e32 v10, s26
	v_mov_b32_e32 v11, s27
	v_fma_f32 v1, s18, v10, v1
	v_fma_f32 v0, s19, v11, v0
	v_readlane_b32 s26, v7, 35
	v_readlane_b32 s27, v9, 35
	v_readlane_b32 s18, v6, 35
	v_readlane_b32 s19, v8, 35
	v_mov_b32_e32 v10, s26
	v_mov_b32_e32 v11, s27
	v_fma_f32 v1, s18, v10, v1
	v_fma_f32 v0, s19, v11, v0
	v_readlane_b32 s26, v7, 36
	v_readlane_b32 s27, v9, 36
	v_readlane_b32 s18, v6, 36
	v_readlane_b32 s19, v8, 36
	v_mov_b32_e32 v10, s26
	v_mov_b32_e32 v11, s27
	v_fma_f32 v1, s18, v10, v1
	v_fma_f32 v0, s19, v11, v0
	v_readlane_b32 s26, v7, 37
	v_readlane_b32 s27, v9, 37
	v_readlane_b32 s18, v6, 37
	v_readlane_b32 s19, v8, 37
	v_mov_b32_e32 v10, s26
	v_mov_b32_e32 v11, s27
	v_fma_f32 v1, s18, v10, v1
	v_fma_f32 v0, s19, v11, v0
	v_readlane_b32 s26, v7, 38
	v_readlane_b32 s27, v9, 38
	v_readlane_b32 s18, v6, 38
	v_readlane_b32 s19, v8, 38
	v_mov_b32_e32 v10, s26
	v_mov_b32_e32 v11, s27
	v_fma_f32 v1, s18, v10, v1
	v_fma_f32 v0, s19, v11, v0
	v_readlane_b32 s26, v7, 39
	v_readlane_b32 s27, v9, 39
	v_readlane_b32 s18, v6, 39
	v_readlane_b32 s19, v8, 39
	v_mov_b32_e32 v10, s26
	v_mov_b32_e32 v11, s27
	v_fma_f32 v1, s18, v10, v1
	v_fma_f32 v0, s19, v11, v0
	v_readlane_b32 s26, v7, 40
	v_readlane_b32 s27, v9, 40
	v_readlane_b32 s18, v6, 40
	v_readlane_b32 s19, v8, 40
	v_mov_b32_e32 v10, s26
	v_mov_b32_e32 v11, s27
	v_fma_f32 v1, s18, v10, v1
	v_fma_f32 v0, s19, v11, v0
	v_readlane_b32 s26, v7, 41
	v_readlane_b32 s27, v9, 41
	v_readlane_b32 s18, v6, 41
	v_readlane_b32 s19, v8, 41
	v_mov_b32_e32 v10, s26
	v_mov_b32_e32 v11, s27
	v_fma_f32 v1, s18, v10, v1
	v_fma_f32 v0, s19, v11, v0
	v_readlane_b32 s26, v7, 42
	v_readlane_b32 s27, v9, 42
	v_readlane_b32 s18, v6, 42
	v_readlane_b32 s19, v8, 42
	v_mov_b32_e32 v10, s26
	v_mov_b32_e32 v11, s27
	v_fma_f32 v1, s18, v10, v1
	v_fma_f32 v0, s19, v11, v0
	v_readlane_b32 s26, v7, 43
	v_readlane_b32 s27, v9, 43
	v_readlane_b32 s18, v6, 43
	v_readlane_b32 s19, v8, 43
	v_mov_b32_e32 v10, s26
	v_mov_b32_e32 v11, s27
	v_fma_f32 v1, s18, v10, v1
	v_fma_f32 v0, s19, v11, v0
	v_readlane_b32 s26, v7, 44
	v_readlane_b32 s27, v9, 44
	v_readlane_b32 s18, v6, 44
	v_readlane_b32 s19, v8, 44
	v_mov_b32_e32 v10, s26
	v_mov_b32_e32 v11, s27
	v_fma_f32 v1, s18, v10, v1
	v_fma_f32 v0, s19, v11, v0
	v_readlane_b32 s26, v7, 45
	v_readlane_b32 s27, v9, 45
	v_readlane_b32 s18, v6, 45
	v_readlane_b32 s19, v8, 45
	v_mov_b32_e32 v10, s26
	v_mov_b32_e32 v11, s27
	v_fma_f32 v1, s18, v10, v1
	v_fma_f32 v0, s19, v11, v0
	v_readlane_b32 s26, v7, 46
	v_readlane_b32 s27, v9, 46
	v_readlane_b32 s18, v6, 46
	v_readlane_b32 s19, v8, 46
	v_mov_b32_e32 v10, s26
	v_mov_b32_e32 v11, s27
	v_fma_f32 v1, s18, v10, v1
	v_fma_f32 v0, s19, v11, v0
	v_readlane_b32 s26, v7, 47
	v_readlane_b32 s27, v9, 47
	v_readlane_b32 s18, v6, 47
	v_readlane_b32 s19, v8, 47
	v_mov_b32_e32 v10, s26
	v_mov_b32_e32 v11, s27
	v_fma_f32 v1, s18, v10, v1
	v_fma_f32 v0, s19, v11, v0
	v_readlane_b32 s26, v7, 48
	v_readlane_b32 s27, v9, 48
	v_readlane_b32 s18, v6, 48
	v_readlane_b32 s19, v8, 48
	v_mov_b32_e32 v10, s26
	v_mov_b32_e32 v11, s27
	v_fma_f32 v1, s18, v10, v1
	v_fma_f32 v0, s19, v11, v0
	v_readlane_b32 s26, v7, 49
	v_readlane_b32 s27, v9, 49
	v_readlane_b32 s18, v6, 49
	v_readlane_b32 s19, v8, 49
	v_mov_b32_e32 v10, s26
	v_mov_b32_e32 v11, s27
	v_fma_f32 v1, s18, v10, v1
	v_fma_f32 v0, s19, v11, v0
	v_readlane_b32 s26, v7, 50
	v_readlane_b32 s27, v9, 50
	v_readlane_b32 s18, v6, 50
	v_readlane_b32 s19, v8, 50
	v_mov_b32_e32 v10, s26
	v_mov_b32_e32 v11, s27
	v_fma_f32 v1, s18, v10, v1
	v_fma_f32 v0, s19, v11, v0
	v_readlane_b32 s26, v7, 51
	v_readlane_b32 s27, v9, 51
	v_readlane_b32 s18, v6, 51
	v_readlane_b32 s19, v8, 51
	v_mov_b32_e32 v10, s26
	v_mov_b32_e32 v11, s27
	v_fma_f32 v1, s18, v10, v1
	v_fma_f32 v0, s19, v11, v0
	v_readlane_b32 s26, v7, 52
	v_readlane_b32 s27, v9, 52
	v_readlane_b32 s18, v6, 52
	v_readlane_b32 s19, v8, 52
	v_mov_b32_e32 v10, s26
	v_mov_b32_e32 v11, s27
	v_fma_f32 v1, s18, v10, v1
	v_fma_f32 v0, s19, v11, v0
	v_readlane_b32 s26, v7, 53
	v_readlane_b32 s27, v9, 53
	v_readlane_b32 s18, v6, 53
	v_readlane_b32 s19, v8, 53
	v_mov_b32_e32 v10, s26
	v_mov_b32_e32 v11, s27
	v_fma_f32 v1, s18, v10, v1
	v_fma_f32 v0, s19, v11, v0
	v_readlane_b32 s26, v7, 54
	v_readlane_b32 s27, v9, 54
	v_readlane_b32 s18, v6, 54
	v_readlane_b32 s19, v8, 54
	v_mov_b32_e32 v10, s26
	v_mov_b32_e32 v11, s27
	v_fma_f32 v1, s18, v10, v1
	v_fma_f32 v0, s19, v11, v0
	v_readlane_b32 s26, v7, 55
	v_readlane_b32 s27, v9, 55
	v_readlane_b32 s18, v6, 55
	v_readlane_b32 s19, v8, 55
	v_mov_b32_e32 v10, s26
	v_mov_b32_e32 v11, s27
	v_fma_f32 v1, s18, v10, v1
	v_fma_f32 v0, s19, v11, v0
	v_readlane_b32 s26, v7, 56
	v_readlane_b32 s27, v9, 56
	v_readlane_b32 s18, v6, 56
	v_readlane_b32 s19, v8, 56
	v_mov_b32_e32 v10, s26
	v_mov_b32_e32 v11, s27
	v_fma_f32 v1, s18, v10, v1
	v_fma_f32 v0, s19, v11, v0
	v_readlane_b32 s26, v7, 57
	v_readlane_b32 s27, v9, 57
	v_readlane_b32 s18, v6, 57
	v_readlane_b32 s19, v8, 57
	v_mov_b32_e32 v10, s26
	v_mov_b32_e32 v11, s27
	v_fma_f32 v1, s18, v10, v1
	v_fma_f32 v0, s19, v11, v0
	v_readlane_b32 s26, v7, 58
	v_readlane_b32 s27, v9, 58
	v_readlane_b32 s18, v6, 58
	v_readlane_b32 s19, v8, 58
	v_mov_b32_e32 v10, s26
	v_mov_b32_e32 v11, s27
	v_fma_f32 v1, s18, v10, v1
	v_fma_f32 v0, s19, v11, v0
	v_readlane_b32 s26, v7, 59
	v_readlane_b32 s27, v9, 59
	v_readlane_b32 s18, v6, 59
	v_readlane_b32 s19, v8, 59
	v_mov_b32_e32 v10, s26
	v_mov_b32_e32 v11, s27
	v_fma_f32 v1, s18, v10, v1
	v_fma_f32 v0, s19, v11, v0
	v_readlane_b32 s26, v7, 60
	v_readlane_b32 s27, v9, 60
	v_readlane_b32 s18, v6, 60
	v_readlane_b32 s19, v8, 60
	v_mov_b32_e32 v10, s26
	v_mov_b32_e32 v11, s27
	v_fma_f32 v1, s18, v10, v1
	v_fma_f32 v0, s19, v11, v0
	v_readlane_b32 s26, v7, 61
	v_readlane_b32 s27, v9, 61
	v_readlane_b32 s18, v6, 61
	v_readlane_b32 s19, v8, 61
	v_mov_b32_e32 v10, s26
	v_mov_b32_e32 v11, s27
	v_fma_f32 v1, s18, v10, v1
	v_fma_f32 v0, s19, v11, v0
	v_readlane_b32 s26, v7, 62
	v_readlane_b32 s27, v9, 62
	v_readlane_b32 s18, v6, 62
	v_readlane_b32 s19, v8, 62
	v_mov_b32_e32 v10, s26
	v_mov_b32_e32 v11, s27
	v_fma_f32 v1, s18, v10, v1
	v_fma_f32 v0, s19, v11, v0
	v_readlane_b32 s26, v7, 63
	v_readlane_b32 s27, v9, 63
	v_readlane_b32 s18, v6, 63
	v_readlane_b32 s19, v8, 63
	v_mov_b32_e32 v10, s26
	v_mov_b32_e32 v11, s27
	v_fma_f32 v1, s18, v10, v1
	v_fma_f32 v0, s19, v11, v0
	v_cvt_f32_i32_e32 v2, s61
	s_mov_b32 s3, 0x3fb8aa3b
	s_mov_b32 s8, 0xc2ce8ed0
	s_mov_b32 s9, 0x42b17218
	v_mul_f32_e32 v2, 0xbe99999a, v2
	v_mul_f32_e32 v3, 0x3fb8aa3b, v2
	v_fma_f32 v4, v2, s3, -v3
	v_rndne_f32_e32 v5, v3
	v_fmac_f32_e32 v4, 0x32a5705f, v2
	v_sub_f32_e32 v3, v3, v5
	v_add_f32_e32 v3, v3, v4
	v_exp_f32_e32 v3, v3
	v_cvt_i32_f32_e32 v4, v5
	v_cmp_ngt_f32_e32 vcc, s8, v2
	s_cmpk_lt_i32 s60, 0x100
	s_cselect_b64 s[68:69], -1, 0
	v_ldexp_f32 v3, v3, v4
	v_cndmask_b32_e32 v3, 0, v3, vcc
	v_cmp_nlt_f32_e32 vcc, s9, v2
	s_mov_b64 s[48:49], -1
	s_nop 0
	v_cndmask_b32_e32 v2, v241, v3, vcc
	v_mov_b32_e32 v3, 0x3f4ccccd
	v_fmamk_f32 v2, v2, 0xbf19999a, v3
	v_mul_f32_e32 v3, 0x3fb8aa3b, v1
	v_rndne_f32_e32 v4, v3
	v_sub_f32_e32 v5, v3, v4
	v_fma_f32 v3, v1, s3, -v3
	v_fmac_f32_e32 v3, 0x32a5705f, v1
	v_add_f32_e32 v3, v5, v3
	v_exp_f32_e32 v3, v3
	v_cvt_i32_f32_e32 v4, v4
	v_cmp_ngt_f32_e32 vcc, s8, v1
	v_sub_f32_e32 v165, 1.0, v2
	v_ldexp_f32 v3, v3, v4
	v_cndmask_b32_e32 v3, 0, v3, vcc
	v_cmp_nlt_f32_e32 vcc, s9, v1
	s_nop 1
	v_cndmask_b32_e32 v1, v241, v3, vcc
	v_mul_f32_e32 v3, 0x3fb8aa3b, v0
	v_rndne_f32_e32 v4, v3
	v_sub_f32_e32 v5, v3, v4
	v_fma_f32 v3, v0, s3, -v3
	v_fmac_f32_e32 v3, 0x32a5705f, v0
	v_add_f32_e32 v3, v5, v3
	v_exp_f32_e32 v3, v3
	v_cvt_i32_f32_e32 v4, v4
	v_cmp_ngt_f32_e32 vcc, s8, v0
	s_lshl_b32 s8, s30, 7
	v_ldexp_f32 v3, v3, v4
	v_cndmask_b32_e32 v3, 0, v3, vcc
	v_cmp_nlt_f32_e32 vcc, s9, v0
	s_ashr_i32 s9, s8, 31
	s_add_u32 s47, s90, 0xe200800
	v_cndmask_b32_e32 v0, v241, v3, vcc
	s_addc_u32 s11, s91, 0
	v_sub_f32_e32 v0, v1, v0
	s_add_u32 s18, s90, 0xe2c0800
	v_add_f32_e32 v164, v2, v0
	s_addc_u32 s42, s91, 0
	s_lshl_b64 s[92:93], s[8:9], 2
	s_branch .LBB0_162

.LBB0_537:
	v_readlane_b32 s6, v253, 0
	v_readlane_b32 s7, v253, 1
	s_nop 1
	v_mov_b32_e32 v10, s6
	v_mov_b32_e32 v11, s7
	s_cmp_gt_i32 s30, 0
	s_mov_b64 s[6:7], -1
	s_cbranch_scc1 .LBB0_540

.LBB0_539:
	v_readlane_b32 s6, v253, 0
	v_readlane_b32 s7, v253, 1
	s_nop 1
	v_mov_b32_e32 v10, s6
	v_mov_b32_e32 v11, s7
	s_mov_b32 s80, s85
	s_mov_b32 s81, s98
	s_mov_b32 s30, s84
	s_cmp_gt_i32 s30, 0
	s_mov_b64 s[6:7], -1
	s_cbranch_scc0 .LBB0_538

.LBB0_567:
	s_mov_b32 s6, -1
	s_nop 0
	v_mbcnt_lo_u32_b32 v0, s6, 0
	v_mbcnt_hi_u32_b32 v0, s6, v0
	v_add_u32_e32 v2, s33, v0
	s_lshl_b32 s6, s60, 2
	s_and_b32 s6, s6, 0xffffff00
	v_ashrrev_i32_e32 v3, 1, v2
	v_lshl_add_u64 v[0:1], s[90:91], 0, v[128:129]
	v_add_u32_e32 v3, s6, v3
	v_lshlrev_b32_e32 v2, 7, v2
	v_mad_i64_i32 v[0:1], s[6:7], s20, v3, v[0:1]
	v_and_b32_e32 v128, 0x80, v2
	v_lshl_add_u64 v[10:11], v[0:1], 0, v[128:129]

.LBB0_572:
	s_and_b64 vcc, exec, s[6:7]
	s_cbranch_vccz .LBB0_658
	s_mov_b32 s3, -1
	s_nop 0
	v_mbcnt_lo_u32_b32 v0, s3, 0
	v_mbcnt_hi_u32_b32 v0, s3, v0
	v_add_u32_e32 v0, s33, v0
	s_waitcnt vmcnt(0)
	s_nop 0
	v_cmp_eq_u32_e32 vcc, 0, v0
	s_barrier
	s_cmp_eq_u32 s33, 0
	s_cbranch_scc1 .Lwarm_skip_0
	global_load_dword v13, v[10:11], off sc0 sc1
.Lwarm_skip_0:
	s_and_saveexec_b64 s[6:7], vcc
	s_cbranch_execz .LBB0_622
	v_readlane_b32 s3, v254, 49
	s_waitcnt vmcnt(0) expcnt(0) lgkmcnt(0)
	s_mov_b64 s[8:9], exec
	v_mov_b32_e32 v3, s3
	ds_read_b32 v2, v3
	v_mbcnt_lo_u32_b32 v0, s8, 0
	v_mbcnt_hi_u32_b32 v1, s9, v0
	v_cmp_eq_u32_e32 vcc, 0, v1
	s_waitcnt lgkmcnt(0)
	v_add_u32_e32 v0, 1, v2
	ds_write_b32 v3, v0
	s_and_saveexec_b64 s[10:11], vcc
	s_cbranch_execz .LBB0_576
	s_bcnt1_i32_b64 s3, s[8:9]
	v_readlane_b32 s8, v253, 62
	v_mov_b32_e32 v3, s3
	v_readlane_b32 s9, v253, 63
	s_nop 4
	global_atomic_add v3, v129, v3, s[8:9] sc0

.LBB0_587:
	s_mov_b32 s3, -1
	s_nop 0
	v_mbcnt_lo_u32_b32 v0, s3, 0
	v_mbcnt_hi_u32_b32 v0, s3, v0
	v_add_u32_e32 v0, s33, v0
	s_waitcnt vmcnt(0)
	s_nop 0
	v_cmp_eq_u32_e32 vcc, 0, v0
	s_barrier
	s_cmp_eq_u32 s33, 0
	s_cbranch_scc1 .Lwarm_skip_1
	global_load_dword v13, v[10:11], off sc0 sc1
.Lwarm_skip_1:
	s_and_saveexec_b64 s[6:7], vcc
	s_cbranch_execz .LBB0_657
	v_readlane_b32 s3, v254, 47
	s_waitcnt vmcnt(0) expcnt(0) lgkmcnt(0)
	s_nop 0
	v_mov_b32_e32 v0, s3
	ds_read_b32 v2, v0
	v_readlane_b32 s3, v254, 48
	s_waitcnt lgkmcnt(0)
	v_cmp_ne_u32_e32 vcc, 0, v2
	v_mov_b32_e32 v0, s3
	ds_read_b32 v0, v0
	s_cbranch_vccnz .LBB0_605
	s_mov_b32 s3, 1
	s_branch .LBB0_591
